# baseline (speedup 1.0000x reference)
; #define LAS __attribute__((address_space(3)))
; DI unsigned f2h(float f) { return (unsigned)__builtin_bit_cast(u16, (_Float16)f); }
; __global__ void __launch_bounds__(512, 2) fwd_megakernel(Args a) {
;     ...
;                     *(LAS u32x4*)(Ks + key * 72 + dc * 8) = kv;
;                     LAS u16* vp = Vt + (dc * 8) * 72 + key;
;                     vp[0 * 72] = (u16)(vv.x & 0xffffu); vp[1 * 72] = (u16)(vv.x >> 16); vp[2 * 72] = (u16)(vv.y & 0xffffu); vp[3 * 72] = (u16)(vv.y >> 16);
;                     vp[4 * 72] = (u16)(vv.z & 0xffffu); vp[5 * 72] = (u16)(vv.z >> 16); vp[6 * 72] = (u16)(vv.w & 0xffffu); vp[7 * 72] = (u16)(vv.w >> 16);
;                 }
;                 __syncthreads();
;                 if (!wdone && k0 < qw + 15) {
;                     f32x4 z[4];
; #pragma unroll
;                     for (int nt = 0; nt < 4; ++nt) { f32x4 c = (f32x4){0.f, 0.f, 0.f, 0.f};
; #pragma unroll
;                         for (int ks = 0; ks < 2; ++ks) { const f16x8 bk = *(const LAS f16x8*)(Ks + (16 * nt + lq) * 72 + 32 * ks + 8 * lg);
;                             c = __builtin_amdgcn_mfma_f32_16x16x32_f16(Aq[ks], bk, c, 0, 0, 0); }
;                         z[nt] = c; }
;                     bool msk[4][4];
; #pragma unroll
;                     for (int nt = 0; nt < 4; ++nt)
; #pragma unroll
;                         for (int j = 0; j < 4; ++j) { const float zz = z[nt][j];
;                             msk[nt][j] = (k0 + 16 * nt + lq) < (qw + 4 * lg + j);
;                             const float sp = fmaxf(zz, 0.f) + __logf(1.f + __expf(-fabsf(zz)));
;                             const float lk = msk[nt][j] ? -sp : 0.f;
;                             Ls[(4 * lg + j) * 72 + 16 * nt + lq] = (u16)f2h(lk); }
.LBB0_416:
	s_xor_b64 s[4:5], s[4:5], -1
	s_andn2_b64 vcc, exec, s[4:5]
	s_mov_b64 s[4:5], -1
	ds_write_b128 v89, v[60:63]
	ds_write_b16 v95, v56 offset:9216
	ds_write_b16_d16_hi v95, v56 offset:9360
	ds_write_b16 v95, v57 offset:9504
	ds_write_b16_d16_hi v95, v57 offset:9648
	ds_write_b16 v95, v58 offset:9792
	ds_write_b16_d16_hi v95, v58 offset:9936
	ds_write_b16 v95, v59 offset:10080
	ds_write_b16_d16_hi v95, v59 offset:10224
	s_waitcnt lgkmcnt(0)
	s_barrier
	s_cbranch_vccnz .LBB0_451
	s_add_i32 s4, s74, 64
	s_cmp_ge_u32 s4, s96
	s_mov_b64 s[4:5], 0
	s_cbranch_scc1 .LBB0_451
	ds_read_b128 v[56:59], v98
	ds_read_b128 v[60:63], v98 offset:64
	v_add_u32_e32 v2, s74, v162
	s_mov_b32 s54, s52
	s_mov_b32 s55, s52
	s_waitcnt lgkmcnt(1)
	v_mfma_f32_16x16x32_f16 v[56:59], v[40:43], v[56:59], 0
	s_mov_b32 s53, s52
	v_mov_b32_e32 v105, 0
	s_waitcnt lgkmcnt(0)
	v_mfma_f32_16x16x32_f16 v[68:71], v[44:47], v[60:63], v[56:59]
	s_nop 3
	ds_read_b128 v[56:59], v98 offset:2304
	ds_read_b128 v[60:63], v98 offset:2368
	ds_read_b128 v[72:75], v98 offset:4608
	ds_read_b128 v[76:79], v98 offset:4672
	v_mul_f32_e64 v1, |v68|, s97
	v_exp_f32_e32 v1, v1
	s_waitcnt lgkmcnt(3)
	v_mfma_f32_16x16x32_f16 v[56:59], v[40:43], v[56:59], 0
	v_add_f32_e32 v1, 1.0, v1
	s_nop 0
	s_waitcnt lgkmcnt(2)
	v_mfma_f32_16x16x32_f16 v[64:67], v[44:47], v[60:63], v[56:59]
	s_nop 3
	ds_read_b128 v[56:59], v98 offset:6912
	ds_read_b128 v[80:83], v98 offset:6976
	s_nop 0
	s_nop 0
	v_log_f32_e32 v1, v1
	s_waitcnt lgkmcnt(3)
	v_mfma_f32_16x16x32_f16 v[60:63], v[40:43], v[72:75], 0
	s_nop 0
	v_max_f32_e32 v3, 0, v68
	v_mul_f32_e32 v72, 0x3f317217, v1
	v_fma_f32 v72, v1, s94, -v72
	v_fmac_f32_e32 v72, 0x3377d1cf, v1
	v_fmac_f32_e32 v72, 0x3f317217, v1
	s_nop 0
	v_mul_f32_e64 v74, |v70|, s97
	v_exp_f32_e32 v74, v74
	v_mov_b32_e32 v1, v72
	s_nop 0
	s_nop 0
	v_add_f32_e32 v1, v3, v1
	v_mul_f32_e64 v3, |v69|, s97
	v_exp_f32_e32 v3, v3
	v_cvt_f16_f32_e64 v1, -v1
	v_add_u32_e32 v72, 64, v2
	v_cmp_lt_u32_e32 vcc, v72, v93
	v_add_f32_e32 v3, 1.0, v3
	s_nop 0
	v_cndmask_b32_e32 v1, 0, v1, vcc
	ds_write_b16 v100, v1 offset:18432
	s_nop 0
	s_nop 0
	v_log_f32_e32 v3, v3
	s_nop 0
	v_max_f32_e32 v1, 0, v69
	s_waitcnt lgkmcnt(3)
	v_mfma_f32_16x16x32_f16 v[60:63], v[44:47], v[76:79], v[60:63]
	v_mul_f32_e32 v73, 0x3f317217, v3
	v_fma_f32 v73, v3, s94, -v73
	v_fmac_f32_e32 v73, 0x3377d1cf, v3
	v_fmac_f32_e32 v73, 0x3f317217, v3
	s_nop 0
	s_waitcnt lgkmcnt(2)
	v_mfma_f32_16x16x32_f16 v[56:59], v[40:43], v[56:59], 0
	v_mov_b32_e32 v3, v73
	s_nop 0
	s_nop 0
	v_add_f32_e32 v1, v1, v3
	v_add_f32_e32 v3, 1.0, v74
	s_nop 0
	v_cvt_f16_f32_e64 v1, -v1
	v_cmp_le_u32_e64 s[4:5], v72, v93
	s_nop 0
	s_nop 0
	v_log_f32_e32 v3, v3
	s_nop 0
	v_max_f32_e32 v73, 0, v70
	v_cndmask_b32_e64 v1, 0, v1, s[4:5]
	v_mul_f32_e32 v74, 0x3f317217, v3
	v_fma_f32 v74, v3, s94, -v74
	v_fmac_f32_e32 v74, 0x3377d1cf, v3
	v_fmac_f32_e32 v74, 0x3f317217, v3
	s_nop 0
	ds_write_b16 v100, v1 offset:18576
	s_waitcnt lgkmcnt(2)
	v_mfma_f32_16x16x32_f16 v[56:59], v[44:47], v[80:83], v[56:59]
	v_mov_b32_e32 v3, v74
	s_nop 0
	s_nop 0
	v_add_f32_e32 v3, v73, v3
	v_mul_f32_e64 v73, |v71|, s97
	v_cvt_f16_f32_e64 v3, -v3
	v_exp_f32_e32 v73, v73
	v_cmp_lt_u32_e64 s[6:7], v72, v103
	v_mul_f32_e64 v74, |v65|, s97
	v_exp_f32_e32 v74, v74
	v_cndmask_b32_e64 v1, 0, v3, s[6:7]
	v_add_f32_e32 v3, 1.0, v73
	s_nop 0
	ds_write_b16 v100, v1 offset:18720
	s_nop 0
	s_nop 0
	s_nop 0
	v_log_f32_e32 v3, v3
	v_max_f32_e32 v1, 0, v71
	v_mov_b64_e32 v[82:83], s[54:55]
	v_mov_b64_e32 v[80:81], s[52:53]
	v_mul_f32_e32 v73, 0x3f317217, v3
	v_fma_f32 v73, v3, s94, -v73
	v_fmac_f32_e32 v73, 0x3377d1cf, v3
	v_fmac_f32_e32 v73, 0x3f317217, v3
	s_nop 0
	s_nop 1
	v_mov_b32_e32 v3, v73
	s_nop 0
	s_nop 0
	v_add_f32_e32 v1, v1, v3
	v_cvt_f16_f32_e64 v1, -v1
	v_mul_f32_e64 v3, |v64|, s97
	v_exp_f32_e32 v3, v3
	v_cmp_lt_u32_e64 s[8:9], v72, v104
	s_nop 0
	v_max_f32_e32 v72, 0, v64
	v_cndmask_b32_e64 v1, 0, v1, s[8:9]
	ds_write_b16 v100, v1 offset:18864
	v_add_f32_e32 v1, 1.0, v3
	s_nop 0
	s_nop 1
	s_nop 0
	s_nop 0
	v_log_f32_e32 v1, v1
	v_add_u32_e32 v3, 0x50, v2
	v_mul_f32_e32 v73, 0x3f317217, v1
	v_fma_f32 v73, v1, s94, -v73
	v_fmac_f32_e32 v73, 0x3377d1cf, v1
	v_fmac_f32_e32 v73, 0x3f317217, v1
	s_nop 0
	s_nop 1
	v_mov_b32_e32 v1, v73
	s_nop 0
	s_nop 0
	v_add_f32_e32 v1, v72, v1
	v_add_f32_e32 v72, 1.0, v74
	s_nop 0
	v_cvt_f16_f32_e64 v1, -v1
	v_cmp_lt_u32_e64 s[10:11], v3, v93
	s_nop 0
	s_nop 0
	v_log_f32_e32 v72, v72
	s_nop 0
	v_max_f32_e32 v73, 0, v65
	v_cndmask_b32_e64 v1, 0, v1, s[10:11]
	v_mul_f32_e32 v74, 0x3f317217, v72
	v_fma_f32 v74, v72, s94, -v74
	v_fmac_f32_e32 v74, 0x3377d1cf, v72
	v_fmac_f32_e32 v74, 0x3f317217, v72
	s_nop 0
	ds_write_b16 v100, v1 offset:18464
	s_nop 0
	v_mov_b32_e32 v72, v74
	s_nop 0
	s_nop 0
	v_add_f32_e32 v72, v73, v72
	v_mul_f32_e64 v73, |v66|, s97
	v_cvt_f16_f32_e64 v72, -v72
	v_exp_f32_e32 v73, v73
	v_cmp_le_u32_e64 s[12:13], v3, v93
	v_mul_f32_e64 v74, |v67|, s97
	v_exp_f32_e32 v74, v74
	v_cndmask_b32_e64 v1, 0, v72, s[12:13]
	v_add_f32_e32 v72, 1.0, v73
	s_nop 0
	ds_write_b16 v100, v1 offset:18608
	s_nop 0
	s_nop 0
	s_nop 0
	v_log_f32_e32 v72, v72
	v_max_f32_e32 v1, 0, v66
	v_mul_f32_e32 v73, 0x3f317217, v72
	v_fma_f32 v73, v72, s94, -v73
	v_fmac_f32_e32 v73, 0x3377d1cf, v72
	v_fmac_f32_e32 v73, 0x3f317217, v72
	s_nop 0
	s_nop 1
	v_mov_b32_e32 v72, v73
	s_nop 0
	s_nop 0
	v_add_f32_e32 v1, v1, v72
	v_add_f32_e32 v72, 1.0, v74
	s_nop 0
	v_cvt_f16_f32_e64 v1, -v1
	v_cmp_lt_u32_e64 s[16:17], v3, v103
	s_nop 0
	s_nop 0
	v_log_f32_e32 v72, v72
	s_nop 0
	v_max_f32_e32 v73, 0, v67
	v_cndmask_b32_e64 v1, 0, v1, s[16:17]
	v_mul_f32_e32 v74, 0x3f317217, v72
; #define LAS __attribute__((address_space(3)))
; DI unsigned f2h(float f) { return (unsigned)__builtin_bit_cast(u16, (_Float16)f); }
; #define LDS_WAIT() asm volatile("s_waitcnt lgkmcnt(0)" ::: "memory")
; __global__ void __launch_bounds__(512, 2) fwd_megakernel(Args a) {
;     ...
;                         for (int j = 0; j < 4; ++j) { const float zz = z[nt][j];
;                             msk[nt][j] = (k0 + 16 * nt + lq) < (qw + 4 * lg + j);
;                             const float sp = fmaxf(zz, 0.f) + __logf(1.f + __expf(-fabsf(zz)));
;                             const float lk = msk[nt][j] ? -sp : 0.f;
;                             Ls[(4 * lg + j) * 72 + 16 * nt + lq] = (u16)f2h(lk); }
;                     LDS_WAIT();
;                     f16x8 Al[2];
; #pragma unroll
;                     for (int ks = 0; ks < 2; ++ks) Al[ks] = *(const LAS f16x8*)(Ls + lq * 72 + 32 * ks + 8 * lg);
;                     LDS_WAIT();
;                     f32x4 cs[4];
; #pragma unroll
;                     for (int nt = 0; nt < 4; ++nt) { f32x4 c = (f32x4){0.f, 0.f, 0.f, 0.f};
; #pragma unroll
;                         for (int ks = 0; ks < 2; ++ks) c = __builtin_amdgcn_mfma_f32_16x16x32_f16(Al[ks], Tb[ks][nt], c, 0, 0, 0);
;                         cs[nt] = c; }
;                     float tot[4];
; #pragma unroll
;                     for (int j = 0; j < 4; ++j) tot[j] = __shfl(cs[0][j], lane & 48);
; #pragma unroll
;                     for (int nt = 0; nt < 4; ++nt)
; #pragma unroll
;                         for (int j = 0; j < 4; ++j) { const float p = msk[nt][j] ? __expf(z[nt][j] + cs[nt][j] + carry[j]) : 0.f;
	v_fma_f32 v74, v72, s94, -v74
	v_fmac_f32_e32 v74, 0x3377d1cf, v72
	v_fmac_f32_e32 v74, 0x3f317217, v72
	s_nop 0
	ds_write_b16 v100, v1 offset:18752
	s_nop 0
	v_mov_b32_e32 v72, v74
	s_nop 0
	s_nop 0
	v_add_f32_e32 v72, v73, v72
	v_mul_f32_e64 v73, |v60|, s97
	v_exp_f32_e32 v73, v73
	v_cvt_f16_f32_e64 v72, -v72
	v_cmp_lt_u32_e64 s[18:19], v3, v104
	v_mul_f32_e64 v74, |v62|, s97
	v_add_f32_e32 v3, 1.0, v73
	s_nop 0
	v_cndmask_b32_e64 v1, 0, v72, s[18:19]
	ds_write_b16 v100, v1 offset:18896
	s_nop 0
	s_nop 0
	v_log_f32_e32 v3, v3
	s_nop 0
	v_max_f32_e32 v1, 0, v60
	v_exp_f32_e32 v74, v74
	v_mul_f32_e32 v72, 0x3f317217, v3
	v_fma_f32 v72, v3, s94, -v72
	v_fmac_f32_e32 v72, 0x3377d1cf, v3
	v_fmac_f32_e32 v72, 0x3f317217, v3
	s_nop 0
	s_nop 1
	v_mov_b32_e32 v3, v72
	s_nop 0
	s_nop 0
	v_add_f32_e32 v1, v1, v3
	v_mul_f32_e64 v3, |v61|, s97
	v_exp_f32_e32 v3, v3
	v_cvt_f16_f32_e64 v1, -v1
	v_add_u32_e32 v72, 0x60, v2
	v_cmp_lt_u32_e64 s[20:21], v72, v93
	v_add_f32_e32 v3, 1.0, v3
	s_nop 0
	v_cndmask_b32_e64 v1, 0, v1, s[20:21]
	ds_write_b16 v100, v1 offset:18496
	s_nop 0
	s_nop 0
	v_log_f32_e32 v3, v3
	s_nop 0
	v_max_f32_e32 v1, 0, v61
	v_add_u32_e32 v2, 0x70, v2
	v_mul_f32_e32 v73, 0x3f317217, v3
	v_fma_f32 v73, v3, s94, -v73
	v_fmac_f32_e32 v73, 0x3377d1cf, v3
	v_fmac_f32_e32 v73, 0x3f317217, v3
	s_nop 0
	s_nop 1
	v_mov_b32_e32 v3, v73
	s_nop 0
	s_nop 0
	v_add_f32_e32 v1, v1, v3
	v_add_f32_e32 v3, 1.0, v74
	s_nop 0
	v_cvt_f16_f32_e64 v1, -v1
	v_cmp_le_u32_e64 s[22:23], v72, v93
	s_nop 0
	s_nop 0
	v_log_f32_e32 v3, v3
	s_nop 0
	v_max_f32_e32 v73, 0, v62
	v_cndmask_b32_e64 v1, 0, v1, s[22:23]
	v_mul_f32_e32 v74, 0x3f317217, v3
	v_fma_f32 v74, v3, s94, -v74
	v_fmac_f32_e32 v74, 0x3377d1cf, v3
	v_fmac_f32_e32 v74, 0x3f317217, v3
	s_nop 0
	ds_write_b16 v100, v1 offset:18640
	s_nop 0
	v_mov_b32_e32 v3, v74
	s_nop 0
	s_nop 0
	v_add_f32_e32 v3, v73, v3
	v_mul_f32_e64 v73, |v63|, s97
	v_cvt_f16_f32_e64 v3, -v3
	v_exp_f32_e32 v73, v73
	v_cmp_lt_u32_e64 s[24:25], v72, v103
	s_nop 1
	v_cndmask_b32_e64 v1, 0, v3, s[24:25]
	v_add_f32_e32 v3, 1.0, v73
	s_nop 0
	ds_write_b16 v100, v1 offset:18784
	s_nop 0
	s_nop 0
	s_nop 0
	v_log_f32_e32 v3, v3
	v_max_f32_e32 v1, 0, v63
	v_mul_f32_e32 v73, 0x3f317217, v3
	v_fma_f32 v73, v3, s94, -v73
	v_fmac_f32_e32 v73, 0x3377d1cf, v3
	v_fmac_f32_e32 v73, 0x3f317217, v3
	s_nop 0
	s_nop 1
	v_mov_b32_e32 v3, v73
	s_nop 0
	s_nop 0
	v_add_f32_e32 v1, v1, v3
	v_cvt_f16_f32_e64 v1, -v1
	v_mul_f32_e64 v3, |v56|, s97
	v_exp_f32_e32 v3, v3
	v_cmp_lt_u32_e64 s[26:27], v72, v104
	v_mul_f32_e64 v73, |v57|, s97
	v_exp_f32_e32 v73, v73
	v_cndmask_b32_e64 v1, 0, v1, s[26:27]
	ds_write_b16 v100, v1 offset:18928
	v_add_f32_e32 v1, 1.0, v3
	s_nop 0
	s_nop 1
	s_nop 0
	s_nop 0
	v_log_f32_e32 v1, v1
	s_nop 0
	v_max_f32_e32 v3, 0, v56
	v_mul_f32_e32 v72, 0x3f317217, v1
	v_fma_f32 v72, v1, s94, -v72
	v_fmac_f32_e32 v72, 0x3377d1cf, v1
	v_fmac_f32_e32 v72, 0x3f317217, v1
	s_nop 0
	s_nop 1
	v_mov_b32_e32 v1, v72
	s_nop 0
	s_nop 0
	v_add_f32_e32 v1, v3, v1
	v_add_f32_e32 v3, 1.0, v73
	s_nop 0
	v_cvt_f16_f32_e64 v1, -v1
	v_cmp_lt_u32_e64 s[28:29], v2, v93
	s_nop 0
	s_nop 0
	v_log_f32_e32 v3, v3
	s_nop 0
	v_max_f32_e32 v72, 0, v57
	v_cndmask_b32_e64 v1, 0, v1, s[28:29]
	v_mul_f32_e32 v73, 0x3f317217, v3
	v_fma_f32 v73, v3, s94, -v73
	v_fmac_f32_e32 v73, 0x3377d1cf, v3
	v_fmac_f32_e32 v73, 0x3f317217, v3
	s_nop 0
	ds_write_b16 v100, v1 offset:18528
	s_nop 0
	v_mov_b32_e32 v3, v73
	s_nop 0
	s_nop 0
	v_add_f32_e32 v3, v72, v3
	v_mul_f32_e64 v72, |v58|, s97
	v_cvt_f16_f32_e64 v3, -v3
	v_exp_f32_e32 v72, v72
	v_cmp_le_u32_e64 s[30:31], v2, v93
	s_nop 1
	v_cndmask_b32_e64 v1, 0, v3, s[30:31]
	v_add_f32_e32 v3, 1.0, v72
	s_nop 0
	ds_write_b16 v100, v1 offset:18672
	s_nop 0
	s_nop 0
	s_nop 0
	v_log_f32_e32 v3, v3
	s_nop 0
	v_max_f32_e32 v1, 0, v58
	v_mul_f32_e32 v72, 0x3f317217, v3
	v_fma_f32 v72, v3, s94, -v72
	v_fmac_f32_e32 v72, 0x3377d1cf, v3
	v_fmac_f32_e32 v72, 0x3f317217, v3
	s_nop 0
	s_nop 1
	v_mov_b32_e32 v3, v72
	v_mul_f32_e64 v72, |v59|, s97
	v_exp_f32_e32 v72, v72
	s_nop 0
	v_add_f32_e32 v1, v1, v3
	v_cvt_f16_f32_e64 v1, -v1
	v_add_f32_e32 v3, 1.0, v72
	s_nop 0
	s_nop 1
	s_nop 0
	s_nop 0
	v_log_f32_e32 v3, v3
	s_nop 0
	v_max_f32_e32 v72, 0, v59
	v_mul_f32_e32 v73, 0x3f317217, v3
	v_fma_f32 v73, v3, s94, -v73
	v_fmac_f32_e32 v73, 0x3377d1cf, v3
	v_fmac_f32_e32 v73, 0x3f317217, v3
	s_nop 0
	s_nop 1
	v_mov_b32_e32 v3, v73
	s_nop 0
	s_nop 0
	v_add_f32_e32 v3, v72, v3
	v_cvt_f16_f32_e64 v3, -v3
	v_cmp_lt_u32_e64 s[36:37], v2, v103
	v_cmp_lt_u32_e64 s[34:35], v2, v104
	v_mov_b32_e32 v2, v0
	v_cndmask_b32_e64 v1, 0, v1, s[36:37]
	ds_write_b16 v100, v1 offset:18816
	v_cndmask_b32_e64 v1, 0, v3, s[34:35]
	ds_write_b16 v100, v1 offset:18960
	s_waitcnt lgkmcnt(0)
	ds_read_b128 v[72:75], v101 offset:18432
	ds_read_b128 v[106:109], v101 offset:18496
	s_waitcnt lgkmcnt(1)
	v_mfma_f32_16x16x32_f16 v[76:79], v[72:75], v[4:7], 0
	v_mov_b32_e32 v1, v0
	v_mov_b32_e32 v3, v0
	s_waitcnt lgkmcnt(0)
	s_waitcnt lgkmcnt(0)
	v_mfma_f32_16x16x32_f16 v[84:87], v[106:109], v[80:83], v[76:79]
	v_mfma_f32_16x16x32_f16 v[76:79], v[72:75], v[8:11], 0
	v_mfma_f32_16x16x32_f16 v[72:75], v[72:75], v[0:3], 0
	s_nop 5
	ds_bpermute_b32 v2, v102, v84
	ds_bpermute_b32 v3, v102, v85
	ds_bpermute_b32 v96, v102, v86
	ds_bpermute_b32 v97, v102, v87
	v_mfma_f32_16x16x32_f16 v[80:83], v[106:109], v[80:83], v[76:79]
	v_mov_b32_e32 v1, 0
	v_mfma_f32_16x16x32_f16 v[76:79], v[106:109], v[12:15], v[72:75]
	v_mfma_f32_16x16x32_f16 v[72:75], v[106:109], v[16:19], v[72:75]
	s_and_saveexec_b64 s[14:15], vcc
	s_cbranch_execz .LBB0_420
	v_add_f32_e32 v68, v68, v84
	v_add_f32_e32 v68, v36, v68
	v_mul_f32_e32 v68, 0x3fb8aa3b, v68
	v_exp_f32_e32 v68, v68
	s_nop 0
	v_cvt_f16_f32_e32 v105, v68
